# P9 epilogue (out += acc): 32-step load-wait-add-store ladder replaced by 16 loads in flight per wave with counted vmcnt
# baseline (speedup 1.0000x reference)
.LBB0_584:
	v_lshl_add_u32 v142, s43, 8, v144
	v_lshl_or_b32 v140, s44, 8, v146
	v_ashrrev_i32_e32 v143, 31, v142
	v_ashrrev_i32_e32 v141, 31, v140
	v_lshlrev_b64 v[150:151], 12, v[142:143]
	v_lshl_add_u64 v[150:151], s[30:31], 0, v[150:151]
	v_lshlrev_b64 v[140:141], 2, v[140:141]
	v_lshl_add_u64 v[154:155], v[150:151], 0, v[140:141]
	s_mov_b64 s[14:15], -1
	s_mov_b32 s51, 0
	s_mov_b32 s50, 0x10000
	v_lshl_add_u64 v[156:157], v[154:155], 0, s[50:51]
	s_mov_b32 s50, 0x20000
	v_lshl_add_u64 v[158:159], v[154:155], 0, s[50:51]
	s_mov_b32 s50, 0x30000
	v_lshl_add_u64 v[160:161], v[154:155], 0, s[50:51]
	s_mov_b32 s50, 0x80000
	v_lshl_add_u64 v[162:163], v[154:155], 0, s[50:51]
	s_mov_b32 s50, 0x90000
	v_lshl_add_u64 v[164:165], v[154:155], 0, s[50:51]
	s_mov_b32 s50, 0xa0000
	v_lshl_add_u64 v[166:167], v[154:155], 0, s[50:51]
	s_mov_b32 s50, 0xb0000
	v_lshl_add_u64 v[168:169], v[154:155], 0, s[50:51]
	global_load_dwordx4 v[176:179], v[154:155], off
	global_load_dwordx4 v[180:183], v[154:155], off offset:64
	global_load_dwordx4 v[184:187], v[154:155], off offset:512
	global_load_dwordx4 v[188:191], v[154:155], off offset:576
	global_load_dwordx4 v[192:195], v[156:157], off
	global_load_dwordx4 v[196:199], v[156:157], off offset:64
	global_load_dwordx4 v[200:203], v[156:157], off offset:512
	global_load_dwordx4 v[204:207], v[156:157], off offset:576
	global_load_dwordx4 v[208:211], v[158:159], off
	global_load_dwordx4 v[212:215], v[158:159], off offset:64
	global_load_dwordx4 v[216:219], v[158:159], off offset:512
	global_load_dwordx4 v[220:223], v[158:159], off offset:576
	global_load_dwordx4 v[224:227], v[160:161], off
	global_load_dwordx4 v[228:231], v[160:161], off offset:64
	global_load_dwordx4 v[232:235], v[160:161], off offset:512
	global_load_dwordx4 v[236:239], v[160:161], off offset:576
	s_waitcnt vmcnt(15)
	v_add_f32_e32 v124, v124, v176
	v_add_f32_e32 v125, v125, v177
	v_add_f32_e32 v126, v126, v178
	v_add_f32_e32 v127, v127, v179
	global_store_dwordx4 v[154:155], v[124:127], off
	global_load_dwordx4 v[176:179], v[162:163], off
	s_waitcnt vmcnt(16)
	v_add_f32_e32 v120, v120, v180
	v_add_f32_e32 v121, v121, v181
	v_add_f32_e32 v122, v122, v182
	v_add_f32_e32 v123, v123, v183
	global_store_dwordx4 v[154:155], v[120:123], off offset:64
	global_load_dwordx4 v[180:183], v[162:163], off offset:64
	s_waitcnt vmcnt(17)
	v_add_f32_e32 v116, v116, v184
	v_add_f32_e32 v117, v117, v185
	v_add_f32_e32 v118, v118, v186
	v_add_f32_e32 v119, v119, v187
	global_store_dwordx4 v[154:155], v[116:119], off offset:512
	global_load_dwordx4 v[184:187], v[162:163], off offset:512
	s_waitcnt vmcnt(18)
	v_add_f32_e32 v108, v108, v188
	v_add_f32_e32 v109, v109, v189
	v_add_f32_e32 v110, v110, v190
	v_add_f32_e32 v111, v111, v191
	global_store_dwordx4 v[154:155], v[108:111], off offset:576
	global_load_dwordx4 v[188:191], v[162:163], off offset:576
	s_waitcnt vmcnt(19)
	v_add_f32_e32 v112, v112, v192
	v_add_f32_e32 v113, v113, v193
	v_add_f32_e32 v114, v114, v194
	v_add_f32_e32 v115, v115, v195
	global_store_dwordx4 v[156:157], v[112:115], off
	global_load_dwordx4 v[192:195], v[164:165], off
	s_waitcnt vmcnt(20)
	v_add_f32_e32 v104, v104, v196
	v_add_f32_e32 v105, v105, v197
	v_add_f32_e32 v106, v106, v198
	v_add_f32_e32 v107, v107, v199
	global_store_dwordx4 v[156:157], v[104:107], off offset:64
	global_load_dwordx4 v[196:199], v[164:165], off offset:64
	s_waitcnt vmcnt(21)
	v_add_f32_e32 v100, v100, v200
	v_add_f32_e32 v101, v101, v201
	v_add_f32_e32 v102, v102, v202
	v_add_f32_e32 v103, v103, v203
	global_store_dwordx4 v[156:157], v[100:103], off offset:512
	global_load_dwordx4 v[200:203], v[164:165], off offset:512
	s_waitcnt vmcnt(22)
	v_add_f32_e32 v96, v96, v204
	v_add_f32_e32 v97, v97, v205
	v_add_f32_e32 v98, v98, v206
	v_add_f32_e32 v99, v99, v207
	global_store_dwordx4 v[156:157], v[96:99], off offset:576
	global_load_dwordx4 v[204:207], v[164:165], off offset:576
	s_waitcnt vmcnt(23)
	v_add_f32_e32 v92, v92, v208
	v_add_f32_e32 v93, v93, v209
	v_add_f32_e32 v94, v94, v210
	v_add_f32_e32 v95, v95, v211
	global_store_dwordx4 v[158:159], v[92:95], off
	global_load_dwordx4 v[208:211], v[166:167], off
	s_waitcnt vmcnt(24)
	v_add_f32_e32 v88, v88, v212
	v_add_f32_e32 v89, v89, v213
	v_add_f32_e32 v90, v90, v214
	v_add_f32_e32 v91, v91, v215
	global_store_dwordx4 v[158:159], v[88:91], off offset:64
	global_load_dwordx4 v[212:215], v[166:167], off offset:64
	s_waitcnt vmcnt(25)
	v_add_f32_e32 v84, v84, v216
	v_add_f32_e32 v85, v85, v217
	v_add_f32_e32 v86, v86, v218
	v_add_f32_e32 v87, v87, v219
	global_store_dwordx4 v[158:159], v[84:87], off offset:512
	global_load_dwordx4 v[216:219], v[166:167], off offset:512
	s_waitcnt vmcnt(26)
	v_add_f32_e32 v80, v80, v220
	v_add_f32_e32 v81, v81, v221
	v_add_f32_e32 v82, v82, v222
	v_add_f32_e32 v83, v83, v223
	global_store_dwordx4 v[158:159], v[80:83], off offset:576
	global_load_dwordx4 v[220:223], v[166:167], off offset:576
	s_waitcnt vmcnt(27)
	v_add_f32_e32 v76, v76, v224
	v_add_f32_e32 v77, v77, v225
	v_add_f32_e32 v78, v78, v226
	v_add_f32_e32 v79, v79, v227
	global_store_dwordx4 v[160:161], v[76:79], off
	global_load_dwordx4 v[224:227], v[168:169], off
	s_waitcnt vmcnt(28)
	v_add_f32_e32 v72, v72, v228
	v_add_f32_e32 v73, v73, v229
	v_add_f32_e32 v74, v74, v230
	v_add_f32_e32 v75, v75, v231
	global_store_dwordx4 v[160:161], v[72:75], off offset:64
	global_load_dwordx4 v[228:231], v[168:169], off offset:64
	s_waitcnt vmcnt(29)
	v_add_f32_e32 v68, v68, v232
	v_add_f32_e32 v69, v69, v233
	v_add_f32_e32 v70, v70, v234
	v_add_f32_e32 v71, v71, v235
	global_store_dwordx4 v[160:161], v[68:71], off offset:512
	global_load_dwordx4 v[232:235], v[168:169], off offset:512
	s_waitcnt vmcnt(30)
	v_add_f32_e32 v64, v64, v236
	v_add_f32_e32 v65, v65, v237
	v_add_f32_e32 v66, v66, v238
	v_add_f32_e32 v67, v67, v239
	global_store_dwordx4 v[160:161], v[64:67], off offset:576
	global_load_dwordx4 v[236:239], v[168:169], off offset:576
	s_waitcnt vmcnt(30)
	v_add_f32_e32 v60, v60, v176
	v_add_f32_e32 v61, v61, v177
	v_add_f32_e32 v62, v62, v178
	v_add_f32_e32 v63, v63, v179
	global_store_dwordx4 v[162:163], v[60:63], off
	s_waitcnt vmcnt(29)
	v_add_f32_e32 v56, v56, v180
	v_add_f32_e32 v57, v57, v181
	v_add_f32_e32 v58, v58, v182
	v_add_f32_e32 v59, v59, v183
	global_store_dwordx4 v[162:163], v[56:59], off offset:64
	s_waitcnt vmcnt(28)
	v_add_f32_e32 v52, v52, v184
	v_add_f32_e32 v53, v53, v185
	v_add_f32_e32 v54, v54, v186
	v_add_f32_e32 v55, v55, v187
	global_store_dwordx4 v[162:163], v[52:55], off offset:512
	s_waitcnt vmcnt(27)
	v_add_f32_e32 v48, v48, v188
	v_add_f32_e32 v49, v49, v189
	v_add_f32_e32 v50, v50, v190
	v_add_f32_e32 v51, v51, v191
	global_store_dwordx4 v[162:163], v[48:51], off offset:576
	s_waitcnt vmcnt(26)
	v_add_f32_e32 v44, v44, v192
	v_add_f32_e32 v45, v45, v193
	v_add_f32_e32 v46, v46, v194
	v_add_f32_e32 v47, v47, v195
	global_store_dwordx4 v[164:165], v[44:47], off
	s_waitcnt vmcnt(25)
	v_add_f32_e32 v40, v40, v196
	v_add_f32_e32 v41, v41, v197
	v_add_f32_e32 v42, v42, v198
	v_add_f32_e32 v43, v43, v199
	global_store_dwordx4 v[164:165], v[40:43], off offset:64
	s_waitcnt vmcnt(24)
	v_add_f32_e32 v36, v36, v200
	v_add_f32_e32 v37, v37, v201
	v_add_f32_e32 v38, v38, v202
	v_add_f32_e32 v39, v39, v203
	global_store_dwordx4 v[164:165], v[36:39], off offset:512
	s_waitcnt vmcnt(23)
	v_add_f32_e32 v32, v32, v204
	v_add_f32_e32 v33, v33, v205
	v_add_f32_e32 v34, v34, v206
	v_add_f32_e32 v35, v35, v207
	global_store_dwordx4 v[164:165], v[32:35], off offset:576
	s_waitcnt vmcnt(22)
	v_add_f32_e32 v28, v28, v208
	v_add_f32_e32 v29, v29, v209
	v_add_f32_e32 v30, v30, v210
	v_add_f32_e32 v31, v31, v211
	global_store_dwordx4 v[166:167], v[28:31], off
	s_waitcnt vmcnt(21)
	v_add_f32_e32 v24, v24, v212
	v_add_f32_e32 v25, v25, v213
	v_add_f32_e32 v26, v26, v214
	v_add_f32_e32 v27, v27, v215
	global_store_dwordx4 v[166:167], v[24:27], off offset:64
	s_waitcnt vmcnt(20)
	v_add_f32_e32 v20, v20, v216
	v_add_f32_e32 v21, v21, v217
	v_add_f32_e32 v22, v22, v218
	v_add_f32_e32 v23, v23, v219
	global_store_dwordx4 v[166:167], v[20:23], off offset:512
	s_waitcnt vmcnt(19)
	v_add_f32_e32 v16, v16, v220
	v_add_f32_e32 v17, v17, v221
	v_add_f32_e32 v18, v18, v222
	v_add_f32_e32 v19, v19, v223
	global_store_dwordx4 v[166:167], v[16:19], off offset:576
	s_waitcnt vmcnt(18)
	v_add_f32_e32 v12, v12, v224
	v_add_f32_e32 v13, v13, v225
	v_add_f32_e32 v14, v14, v226
	v_add_f32_e32 v15, v15, v227
	global_store_dwordx4 v[168:169], v[12:15], off
	s_waitcnt vmcnt(17)
	v_add_f32_e32 v8, v8, v228
	v_add_f32_e32 v9, v9, v229
	v_add_f32_e32 v10, v10, v230
	v_add_f32_e32 v11, v11, v231
	global_store_dwordx4 v[168:169], v[8:11], off offset:64
	s_waitcnt vmcnt(16)
	v_add_f32_e32 v4, v4, v232
	v_add_f32_e32 v5, v5, v233
	v_add_f32_e32 v6, v6, v234
	v_add_f32_e32 v7, v7, v235
	global_store_dwordx4 v[168:169], v[4:7], off offset:512
	s_waitcnt vmcnt(15)
	v_add_f32_e32 v0, v0, v236
	v_add_f32_e32 v1, v1, v237
	v_add_f32_e32 v2, v2, v238
	v_add_f32_e32 v3, v3, v239
	global_store_dwordx4 v[168:169], v[0:3], off offset:576
	s_andn2_b64 vcc, exec, s[0:1]
	s_cbranch_vccnz .LBB0_573
	s_andn2_b64 vcc, exec, s[4:5]
	s_cbranch_vccnz .LBB0_572
	s_barrier
	s_branch .LBB0_572
